# same as the pipelined-epilogue version but the FF1 first-K-step wait lowered to vmcnt(16) so it still covers the prefetch DMAs now that the FF1 epilogue issues 16 stores
# baseline (speedup 1.0000x reference)
; template <int MI, bool SWAP, class Epi> ...
;     ...
;     for (int kt = 0; kt < nk; ++kt) {
;         if (kt + 1 < nk && !(prefetched && kt == 0)) { if (MI == 8) asm volatile("s_waitcnt vmcnt(6)\n\ts_barrier" ::: "memory"); else if (MI == 4) asm volatile("s_waitcnt vmcnt(4)\n\ts_barrier" ::: "memory"); else asm volatile("s_waitcnt vmcnt(3)\n\ts_barrier" ::: "memory"); }
;         else asm volatile("s_waitcnt vmcnt(0)\n\ts_barrier" ::: "memory");
.LBB0_2185:
	s_andn2_b64 vcc, exec, s[0:1]
	s_cbranch_vccnz .LBB0_2187
	s_waitcnt vmcnt(16)
	s_barrier
